# IN GEMM: next-next tile order arithmetic precomputed in the peeled first K-iteration (scalar ops between MFMAs); tile header only copies it
# speedup vs baseline: 1.0046x; 1.0012x over previous
.LBB0_137:
	s_add_i32 s54, s54, 1
	s_cmp_eq_u32 s54, 1
	s_cbranch_scc1 .Lhdr_full
	s_mov_b64 s[6:7], s[88:89]
	s_mov_b32 s24, s80
	s_mov_b32 s26, s81
	s_branch .LBB0_139
.Lhdr_full:
	s_mul_i32 s0, s23, s54
	s_mul_hi_u32 s1, s22, s54
	s_add_i32 s1, s1, s0
	s_mul_i32 s0, s22, s54
	s_add_u32 s0, s0, s2
	s_addc_u32 s1, s1, s35
	v_cmp_gt_i64_e32 vcc, s[0:1], v[150:151]
	v_cmp_lt_i64_e64 s[6:7], s[0:1], v[148:149]
	s_cbranch_vccnz .LBB0_139
	s_ashr_i32 s1, s0, 31
	s_lshr_b32 s1, s1, 29
	s_add_i32 s1, s0, s1
	s_ashr_i32 s14, s1, 3
	s_and_b32 s1, s1, -8
	s_sub_i32 s0, s0, s1
	s_cmp_lt_i32 s0, 0
	s_cselect_b32 s1, s67, 0x1c0
	s_mul_i32 s0, s0, s1
	s_add_i32 s0, s0, s14
	s_mul_hi_i32 s1, s0, 0x92492493
	s_add_i32 s1, s1, s0
	s_lshr_b32 s14, s1, 31
	s_ashr_i32 s1, s1, 7
	s_add_i32 s1, s1, s14
	s_lshl_b32 s14, s1, 3
	s_sub_i32 s15, 0x80, s14
	s_min_i32 s15, s15, 8
	s_abs_i32 s24, s15
	v_cvt_f32_u32_e32 v0, s24
	s_sub_i32 s26, 0, s24
	s_mulk_i32 s1, 0xe0
	s_sub_i32 s0, s0, s1
	v_rcp_iflag_f32_e32 v0, v0
	s_abs_i32 s1, s0
	s_xor_b32 s25, s0, s15
	s_ashr_i32 s25, s25, 31
	v_mul_f32_e32 v0, 0x4f7ffffe, v0
	v_cvt_u32_f32_e32 v0, v0
	s_nop 0
	v_readfirstlane_b32 s27, v0
	s_mul_i32 s26, s26, s27
	s_mul_hi_u32 s26, s27, s26
	s_add_i32 s27, s27, s26
	s_mul_hi_u32 s26, s1, s27
	s_mul_i32 s27, s26, s24
	s_sub_i32 s1, s1, s27
	s_add_i32 s57, s26, 1
	s_sub_i32 s27, s1, s24
	s_cmp_ge_u32 s1, s24
	s_cselect_b32 s26, s57, s26
	s_cselect_b32 s1, s27, s1
	s_add_i32 s27, s26, 1
	s_cmp_ge_u32 s1, s24
	s_cselect_b32 s1, s27, s26
	s_xor_b32 s1, s1, s25
	s_sub_i32 s24, s1, s25
	s_mul_i32 s1, s24, s15
	s_sub_i32 s0, s0, s1
	s_add_i32 s26, s14, s0

.Lin_zskip:
	s_add_u32 s10, s8, 0xfff80080
	s_addc_u32 s11, s9, -1
	s_add_i32 s60, 0, 0x10000
	s_cmp_eq_u32 s59, 28
	s_cselect_b32 s15, s0, s11
	s_cselect_b32 s14, s1, s10
	v_add_u32_e32 v0, s60, v167
	s_cselect_b32 s11, s25, s58
	s_cselect_b32 s10, s27, s57
	s_add_i32 s62, 0, 0x14000
	ds_read_b128 v[130:133], v0
	ds_read_b128 v[158:161], v0 offset:1024
	ds_read_b128 v[162:165], v0 offset:2048
	ds_read_b128 v[170:173], v0 offset:3072
	v_add_u32_e32 v0, s62, v167
	ds_read_b128 v[174:177], v0
	ds_read_b128 v[178:181], v0 offset:1024
	ds_read_b128 v[182:185], v0 offset:2048
	ds_read_b128 v[186:189], v0 offset:3072
	s_mov_b32 m0, s52
	s_nop 0
	global_load_lds_dwordx4 v140, s[74:75]
	s_mov_b32 m0, s53
	s_nop 0
	global_load_lds_dwordx4 v136, s[74:75]
	s_add_i32 m0, s48, 0xc000
	ds_read_b128 v[190:193], v169
	ds_read_b128 v[194:197], v169 offset:1024
	ds_read_b128 v[198:201], v169 offset:2048
	ds_read_b128 v[216:219], v169 offset:3072
	ds_read_b128 v[220:223], v169 offset:4096
	ds_read_b128 v[224:227], v169 offset:5120
	ds_read_b128 v[228:231], v169 offset:6144
	ds_read_b128 v[232:235], v169 offset:7168
	global_load_lds_dwordx4 v156, s[8:9]
	s_add_i32 m0, s48, 0xe000
	s_nop 0
	global_load_lds_dwordx4 v146, s[8:9]
	s_waitcnt vmcnt(8)
	s_waitcnt lgkmcnt(0)
	s_barrier
	s_setprio 1
	s_waitcnt lgkmcnt(0)
	v_mfma_f32_16x16x32_bf16 v[126:129], v[130:133], v[190:193], 0
	s_add_i32 s101, s54, 1
	s_mul_i32 s76, s23, s101
	s_mul_hi_u32 s77, s22, s101
	v_mfma_f32_16x16x32_bf16 v[122:125], v[162:165], v[190:193], 0
	s_add_i32 s77, s77, s76
	s_mul_i32 s76, s22, s101
	s_add_u32 s76, s76, s2
	v_mfma_f32_16x16x32_bf16 v[110:113], v[130:133], v[198:201], 0
	s_addc_u32 s77, s77, s35
	v_cmp_lt_i64_e64 s[88:89], s[76:77], v[148:149]
	s_ashr_i32 s77, s76, 31
	v_mfma_f32_16x16x32_bf16 v[106:109], v[162:165], v[198:201], 0
	s_lshr_b32 s77, s77, 29
	s_add_i32 s77, s76, s77
	s_ashr_i32 s32, s77, 3
	v_mfma_f32_16x16x32_bf16 v[94:97], v[130:133], v[220:223], 0
	s_and_b32 s77, s77, -8
	s_sub_i32 s76, s76, s77
	s_cmp_lt_i32 s76, 0
	v_mfma_f32_16x16x32_bf16 v[90:93], v[162:165], v[220:223], 0
	s_cselect_b32 s77, s67, 0x1c0
	s_mul_i32 s76, s76, s77
	s_add_i32 s76, s76, s32
	v_mfma_f32_16x16x32_bf16 v[78:81], v[130:133], v[228:231], 0
	s_mul_hi_i32 s77, s76, 0x92492493
	s_add_i32 s77, s77, s76
	s_lshr_b32 s32, s77, 31
	v_mfma_f32_16x16x32_bf16 v[74:77], v[162:165], v[228:231], 0
	s_ashr_i32 s77, s77, 7
	s_add_i32 s77, s77, s32
	s_lshl_b32 s32, s77, 3
	v_mfma_f32_16x16x32_bf16 v[126:129], v[158:161], v[194:197], v[126:129]
	s_sub_i32 s34, 0x80, s32
	s_min_i32 s34, s34, 8
	s_abs_i32 s80, s34
	v_mfma_f32_16x16x32_bf16 v[122:125], v[170:173], v[194:197], v[122:125]
	v_cvt_f32_u32_e32 v157, s80
	s_sub_i32 s81, 0, s80
	s_mulk_i32 s77, 0xe0
	v_mfma_f32_16x16x32_bf16 v[110:113], v[158:161], v[216:219], v[110:113]
	s_sub_i32 s76, s76, s77
	v_rcp_iflag_f32_e32 v157, v157
	s_abs_i32 s77, s76
	v_mfma_f32_16x16x32_bf16 v[106:109], v[170:173], v[216:219], v[106:109]
	s_xor_b32 s100, s76, s34
	s_ashr_i32 s100, s100, 31
	v_mul_f32_e32 v157, 0x4f7ffffe, v157
	v_mfma_f32_16x16x32_bf16 v[94:97], v[158:161], v[224:227], v[94:97]
	v_cvt_u32_f32_e32 v157, v157
	s_nop 0
	v_readfirstlane_b32 s101, v157
	v_mfma_f32_16x16x32_bf16 v[90:93], v[170:173], v[224:227], v[90:93]
	s_mul_i32 s81, s81, s101
	s_mul_hi_u32 s81, s101, s81
	s_add_i32 s101, s101, s81
	v_mfma_f32_16x16x32_bf16 v[78:81], v[158:161], v[232:235], v[78:81]
	s_mul_hi_u32 s81, s77, s101
	s_mul_i32 s101, s81, s80
	s_sub_i32 s77, s77, s101
	v_mfma_f32_16x16x32_bf16 v[74:77], v[170:173], v[232:235], v[74:77]
	s_add_i32 vcc_lo, s81, 1
	s_sub_i32 s101, s77, s80
	s_cmp_ge_u32 s77, s80
	s_setprio 0
	s_setprio 1
	v_mfma_f32_16x16x32_bf16 v[118:121], v[174:177], v[190:193], 0
	s_cselect_b32 s81, vcc_lo, s81
	s_cselect_b32 s77, s101, s77
	s_add_i32 s101, s81, 1
	v_mfma_f32_16x16x32_bf16 v[114:117], v[182:185], v[190:193], 0
	s_cmp_ge_u32 s77, s80
	s_cselect_b32 s77, s101, s81
	s_xor_b32 s77, s77, s100
	v_mfma_f32_16x16x32_bf16 v[102:105], v[174:177], v[198:201], 0
	s_sub_i32 s80, s77, s100
	s_mul_i32 s77, s80, s34
	s_sub_i32 s76, s76, s77
	v_mfma_f32_16x16x32_bf16 v[98:101], v[182:185], v[198:201], 0
	s_add_i32 s81, s32, s76
	v_mfma_f32_16x16x32_bf16 v[86:89], v[174:177], v[220:223], 0
	v_mfma_f32_16x16x32_bf16 v[82:85], v[182:185], v[220:223], 0
	v_mfma_f32_16x16x32_bf16 v[70:73], v[174:177], v[228:231], 0
	v_mfma_f32_16x16x32_bf16 v[66:69], v[182:185], v[228:231], 0
	v_mfma_f32_16x16x32_bf16 v[118:121], v[178:181], v[194:197], v[118:121]
	v_mfma_f32_16x16x32_bf16 v[114:117], v[186:189], v[194:197], v[114:117]
	v_mfma_f32_16x16x32_bf16 v[102:105], v[178:181], v[216:219], v[102:105]
	v_mfma_f32_16x16x32_bf16 v[98:101], v[186:189], v[216:219], v[98:101]
	v_mfma_f32_16x16x32_bf16 v[86:89], v[178:181], v[224:227], v[86:89]
	v_mfma_f32_16x16x32_bf16 v[82:85], v[186:189], v[224:227], v[82:85]
	v_mfma_f32_16x16x32_bf16 v[70:73], v[178:181], v[232:235], v[70:73]
	v_mfma_f32_16x16x32_bf16 v[66:69], v[186:189], v[232:235], v[66:69]
	s_setprio 0
	s_barrier
	s_add_i32 s60, s60, s29
	s_add_u32 s72, s10, s44
	s_addc_u32 s73, s11, s45
	s_mov_b32 m0, s60
	ds_read_b128 v[190:193], v169 offset:16384
	ds_read_b128 v[194:197], v169 offset:17408
	ds_read_b128 v[198:201], v169 offset:18432
	ds_read_b128 v[216:219], v169 offset:19456
	ds_read_b128 v[220:223], v169 offset:20480
	ds_read_b128 v[224:227], v169 offset:21504
	ds_read_b128 v[228:231], v169 offset:22528
	ds_read_b128 v[232:235], v169 offset:23552
	global_load_lds_dwordx4 v138, s[10:11]
	s_add_i32 m0, s60, 0x2000
	s_add_u32 s60, s10, 0x80000
	s_addc_u32 s61, s11, 0
	s_add_i32 s62, s62, s29
	global_load_lds_dwordx4 v134, s[10:11]
	s_mov_b32 m0, s62
	s_add_u32 s74, s14, s44
	s_addc_u32 s75, s15, s45
	global_load_lds_dwordx4 v138, s[60:61]
	s_add_i32 m0, s62, 0x2000
	s_nop 0
	global_load_lds_dwordx4 v134, s[60:61]
	s_waitcnt vmcnt(6)
	s_waitcnt lgkmcnt(0)
	s_barrier
	s_setprio 1
	s_waitcnt lgkmcnt(0)
	v_mfma_f32_16x16x32_bf16 v[62:65], v[130:133], v[190:193], 0
	v_mfma_f32_16x16x32_bf16 v[58:61], v[162:165], v[190:193], 0
	v_mfma_f32_16x16x32_bf16 v[46:49], v[130:133], v[198:201], 0
	v_mfma_f32_16x16x32_bf16 v[42:45], v[162:165], v[198:201], 0
	v_mfma_f32_16x16x32_bf16 v[30:33], v[130:133], v[220:223], 0
	v_mfma_f32_16x16x32_bf16 v[26:29], v[162:165], v[220:223], 0
	v_mfma_f32_16x16x32_bf16 v[14:17], v[130:133], v[228:231], 0
	v_mfma_f32_16x16x32_bf16 v[10:13], v[162:165], v[228:231], 0
	v_mfma_f32_16x16x32_bf16 v[62:65], v[158:161], v[194:197], v[62:65]
	v_mfma_f32_16x16x32_bf16 v[58:61], v[170:173], v[194:197], v[58:61]
	v_mfma_f32_16x16x32_bf16 v[46:49], v[158:161], v[216:219], v[46:49]
	v_mfma_f32_16x16x32_bf16 v[42:45], v[170:173], v[216:219], v[42:45]
	v_mfma_f32_16x16x32_bf16 v[30:33], v[158:161], v[224:227], v[30:33]
	v_mfma_f32_16x16x32_bf16 v[26:29], v[170:173], v[224:227], v[26:29]
	v_mfma_f32_16x16x32_bf16 v[14:17], v[158:161], v[232:235], v[14:17]
	v_mfma_f32_16x16x32_bf16 v[10:13], v[170:173], v[232:235], v[10:13]
	s_setprio 0
	s_setprio 1
	v_mfma_f32_16x16x32_bf16 v[54:57], v[174:177], v[190:193], 0
	v_mfma_f32_16x16x32_bf16 v[50:53], v[182:185], v[190:193], 0
	v_mfma_f32_16x16x32_bf16 v[38:41], v[174:177], v[198:201], 0
	v_mfma_f32_16x16x32_bf16 v[34:37], v[182:185], v[198:201], 0
	v_mfma_f32_16x16x32_bf16 v[22:25], v[174:177], v[220:223], 0
	v_mfma_f32_16x16x32_bf16 v[18:21], v[182:185], v[220:223], 0
	v_mfma_f32_16x16x32_bf16 v[6:9], v[174:177], v[228:231], 0
	v_mfma_f32_16x16x32_bf16 v[2:5], v[182:185], v[228:231], 0
	v_mfma_f32_16x16x32_bf16 v[54:57], v[178:181], v[194:197], v[54:57]
	v_mfma_f32_16x16x32_bf16 v[50:53], v[186:189], v[194:197], v[50:53]
	v_mfma_f32_16x16x32_bf16 v[38:41], v[178:181], v[216:219], v[38:41]
	v_mfma_f32_16x16x32_bf16 v[34:37], v[186:189], v[216:219], v[34:37]
	v_mfma_f32_16x16x32_bf16 v[22:25], v[178:181], v[224:227], v[22:25]
	v_mfma_f32_16x16x32_bf16 v[18:21], v[186:189], v[224:227], v[18:21]
	v_mfma_f32_16x16x32_bf16 v[6:9], v[178:181], v[232:235], v[6:9]
	v_mfma_f32_16x16x32_bf16 v[2:5], v[186:189], v[232:235], v[2:5]
	s_setprio 0
	s_barrier
	s_add_i32 s60, 0, 0x18000
	v_add_u32_e32 v0, s60, v167
	s_add_i32 s61, 0, 0x1c000
	ds_read_b128 v[130:133], v0
	ds_read_b128 v[158:161], v0 offset:1024
	ds_read_b128 v[162:165], v0 offset:2048
	ds_read_b128 v[170:173], v0 offset:3072
	v_add_u32_e32 v0, s61, v167
	ds_read_b128 v[174:177], v0
	ds_read_b128 v[178:181], v0 offset:1024
	ds_read_b128 v[182:185], v0 offset:2048
	ds_read_b128 v[186:189], v0 offset:3072
	s_mov_b32 m0, s48
	s_nop 0
	global_load_lds_dwordx4 v140, s[14:15]
	s_mov_b32 m0, s49
	s_nop 0
	global_load_lds_dwordx4 v136, s[14:15]
	s_add_u32 s14, s14, 0x80000
	s_addc_u32 s15, s15, 0
	s_mov_b32 m0, s50
	ds_read_b128 v[190:193], v169 offset:32768
	ds_read_b128 v[194:197], v169 offset:33792
	ds_read_b128 v[198:201], v169 offset:34816
	ds_read_b128 v[216:219], v169 offset:35840
	ds_read_b128 v[220:223], v169 offset:36864
	ds_read_b128 v[224:227], v169 offset:37888
	ds_read_b128 v[228:231], v169 offset:38912
	ds_read_b128 v[232:235], v169 offset:39936
	global_load_lds_dwordx4 v140, s[14:15]
	s_mov_b32 m0, s51
	s_nop 0
	global_load_lds_dwordx4 v136, s[14:15]
	s_waitcnt vmcnt(8)
	s_waitcnt lgkmcnt(0)
	s_barrier
	s_setprio 1
	s_waitcnt lgkmcnt(0)
	v_mfma_f32_16x16x32_bf16 v[126:129], v[130:133], v[190:193], v[126:129]
	v_mfma_f32_16x16x32_bf16 v[122:125], v[162:165], v[190:193], v[122:125]
	v_mfma_f32_16x16x32_bf16 v[110:113], v[130:133], v[198:201], v[110:113]
	v_mfma_f32_16x16x32_bf16 v[106:109], v[162:165], v[198:201], v[106:109]
	v_mfma_f32_16x16x32_bf16 v[94:97], v[130:133], v[220:223], v[94:97]
	v_mfma_f32_16x16x32_bf16 v[90:93], v[162:165], v[220:223], v[90:93]
	v_mfma_f32_16x16x32_bf16 v[78:81], v[130:133], v[228:231], v[78:81]
	v_mfma_f32_16x16x32_bf16 v[74:77], v[162:165], v[228:231], v[74:77]
	v_mfma_f32_16x16x32_bf16 v[126:129], v[158:161], v[194:197], v[126:129]
	v_mfma_f32_16x16x32_bf16 v[122:125], v[170:173], v[194:197], v[122:125]
	v_mfma_f32_16x16x32_bf16 v[110:113], v[158:161], v[216:219], v[110:113]
	v_mfma_f32_16x16x32_bf16 v[106:109], v[170:173], v[216:219], v[106:109]
	v_mfma_f32_16x16x32_bf16 v[94:97], v[158:161], v[224:227], v[94:97]
	v_mfma_f32_16x16x32_bf16 v[90:93], v[170:173], v[224:227], v[90:93]
	v_mfma_f32_16x16x32_bf16 v[78:81], v[158:161], v[232:235], v[78:81]
	v_mfma_f32_16x16x32_bf16 v[74:77], v[170:173], v[232:235], v[74:77]
	s_setprio 0
	s_setprio 1
	v_mfma_f32_16x16x32_bf16 v[118:121], v[174:177], v[190:193], v[118:121]
	v_mfma_f32_16x16x32_bf16 v[114:117], v[182:185], v[190:193], v[114:117]
	v_mfma_f32_16x16x32_bf16 v[102:105], v[174:177], v[198:201], v[102:105]
	v_mfma_f32_16x16x32_bf16 v[98:101], v[182:185], v[198:201], v[98:101]
	v_mfma_f32_16x16x32_bf16 v[86:89], v[174:177], v[220:223], v[86:89]
	v_mfma_f32_16x16x32_bf16 v[82:85], v[182:185], v[220:223], v[82:85]
	v_mfma_f32_16x16x32_bf16 v[70:73], v[174:177], v[228:231], v[70:73]
	v_mfma_f32_16x16x32_bf16 v[66:69], v[182:185], v[228:231], v[66:69]
	v_mfma_f32_16x16x32_bf16 v[118:121], v[178:181], v[194:197], v[118:121]
	v_mfma_f32_16x16x32_bf16 v[114:117], v[186:189], v[194:197], v[114:117]
	v_mfma_f32_16x16x32_bf16 v[102:105], v[178:181], v[216:219], v[102:105]
	v_mfma_f32_16x16x32_bf16 v[98:101], v[186:189], v[216:219], v[98:101]
	v_mfma_f32_16x16x32_bf16 v[86:89], v[178:181], v[224:227], v[86:89]
	v_mfma_f32_16x16x32_bf16 v[82:85], v[186:189], v[224:227], v[82:85]
	v_mfma_f32_16x16x32_bf16 v[70:73], v[178:181], v[232:235], v[70:73]
	v_mfma_f32_16x16x32_bf16 v[66:69], v[186:189], v[232:235], v[66:69]
	s_setprio 0
	s_barrier
	s_add_i32 s14, s60, s29
	s_mov_b32 m0, s14
	ds_read_b128 v[190:193], v169 offset:49152
	ds_read_b128 v[194:197], v169 offset:50176
	ds_read_b128 v[198:201], v169 offset:51200
	ds_read_b128 v[216:219], v169 offset:52224
	ds_read_b128 v[220:223], v169 offset:53248
	ds_read_b128 v[224:227], v169 offset:54272
	ds_read_b128 v[228:231], v169 offset:55296
	ds_read_b128 v[232:235], v169 offset:56320
	global_load_lds_dwordx4 v138, s[72:73]
	s_add_i32 m0, s14, 0x2000
	s_add_u32 s10, s10, 0x80080
	s_addc_u32 s11, s11, 0
	s_add_i32 s14, s61, s29
	global_load_lds_dwordx4 v134, s[72:73]
	s_mov_b32 m0, s14
	s_nop 0
	global_load_lds_dwordx4 v138, s[10:11]
	s_add_i32 m0, s14, 0x2000
	s_nop 0
	global_load_lds_dwordx4 v134, s[10:11]
	s_waitcnt vmcnt(6)
	s_waitcnt lgkmcnt(0)
	s_barrier
	s_setprio 1
	s_waitcnt lgkmcnt(0)
	v_mfma_f32_16x16x32_bf16 v[62:65], v[130:133], v[190:193], v[62:65]
	v_mfma_f32_16x16x32_bf16 v[58:61], v[162:165], v[190:193], v[58:61]
	v_mfma_f32_16x16x32_bf16 v[46:49], v[130:133], v[198:201], v[46:49]
	v_mfma_f32_16x16x32_bf16 v[42:45], v[162:165], v[198:201], v[42:45]
	v_mfma_f32_16x16x32_bf16 v[30:33], v[130:133], v[220:223], v[30:33]
	v_mfma_f32_16x16x32_bf16 v[26:29], v[162:165], v[220:223], v[26:29]
	v_mfma_f32_16x16x32_bf16 v[14:17], v[130:133], v[228:231], v[14:17]
	v_mfma_f32_16x16x32_bf16 v[10:13], v[162:165], v[228:231], v[10:13]
	v_mfma_f32_16x16x32_bf16 v[62:65], v[158:161], v[194:197], v[62:65]
	v_mfma_f32_16x16x32_bf16 v[58:61], v[170:173], v[194:197], v[58:61]
	v_mfma_f32_16x16x32_bf16 v[46:49], v[158:161], v[216:219], v[46:49]
	v_mfma_f32_16x16x32_bf16 v[42:45], v[170:173], v[216:219], v[42:45]
	v_mfma_f32_16x16x32_bf16 v[30:33], v[158:161], v[224:227], v[30:33]
	v_mfma_f32_16x16x32_bf16 v[26:29], v[170:173], v[224:227], v[26:29]
	v_mfma_f32_16x16x32_bf16 v[14:17], v[158:161], v[232:235], v[14:17]
	v_mfma_f32_16x16x32_bf16 v[10:13], v[170:173], v[232:235], v[10:13]
	s_setprio 0
	s_setprio 1
	v_mfma_f32_16x16x32_bf16 v[54:57], v[174:177], v[190:193], v[54:57]
	v_mfma_f32_16x16x32_bf16 v[50:53], v[182:185], v[190:193], v[50:53]
	v_mfma_f32_16x16x32_bf16 v[38:41], v[174:177], v[198:201], v[38:41]
	v_mfma_f32_16x16x32_bf16 v[34:37], v[182:185], v[198:201], v[34:37]
	v_mfma_f32_16x16x32_bf16 v[22:25], v[174:177], v[220:223], v[22:25]
	v_mfma_f32_16x16x32_bf16 v[18:21], v[182:185], v[220:223], v[18:21]
	v_mfma_f32_16x16x32_bf16 v[6:9], v[174:177], v[228:231], v[6:9]
	v_mfma_f32_16x16x32_bf16 v[2:5], v[182:185], v[228:231], v[2:5]
	v_mfma_f32_16x16x32_bf16 v[54:57], v[178:181], v[194:197], v[54:57]
	v_mfma_f32_16x16x32_bf16 v[50:53], v[186:189], v[194:197], v[50:53]
	v_mfma_f32_16x16x32_bf16 v[38:41], v[178:181], v[216:219], v[38:41]
	v_mfma_f32_16x16x32_bf16 v[34:37], v[186:189], v[216:219], v[34:37]
	v_mfma_f32_16x16x32_bf16 v[22:25], v[178:181], v[224:227], v[22:25]
	v_mfma_f32_16x16x32_bf16 v[18:21], v[186:189], v[224:227], v[18:21]
	v_mfma_f32_16x16x32_bf16 v[6:9], v[178:181], v[232:235], v[6:9]
	v_mfma_f32_16x16x32_bf16 v[2:5], v[186:189], v[232:235], v[2:5]
	s_setprio 0
	s_barrier
	s_add_i32 s59, s59, 2
	s_add_u32 s57, s57, 0x100
	s_addc_u32 s58, s58, 0
	s_add_u32 s8, s8, 0x100
	s_addc_u32 s9, s9, 0
	s_cmp_gt_u32 s59, 29
